# nt on the residual loads of all four residual GEMM epilogues (phases 6, 9, 15, 18): the residual is read once and overwritten in place
# baseline (speedup 1.0000x reference)
; #define PH(k) case k: if (ONLY_PHASE >= 0 && ONLY_PHASE != k) break;
; template <int ph> DI void run_phase(const Ctx& c, char* smem) {
;     ...
;     PH(9) gemm_phase(smem, (const bf16_t*)(ws + OFF_R1), 4096, 1 << 30, XN, 1024, (const bf16_t*)(ws + OFF_W2), 4096, 8, EpiResid{p.out, p.out}, TIDX); break;
.Lg9_epi:
	s_nop 7
	s_nop 7
	s_lshl_b32 s10, s16, 12
	s_lshl_b32 s9, s11, 2
	s_add_u32 s10, s10, s9
	s_add_u32 s4, s6, s10
	s_addc_u32 s5, s7, 0
	s_lshl_b32 s10, s16, 12
	s_lshl_b32 s9, s11, 2
	s_add_u32 s10, s10, s9
	s_add_u32 s0, s6, s10
	s_addc_u32 s1, s7, 0
	ds_write_b128 v245, v[0:3]
	ds_write_b128 v245, v[4:7] offset:64
	ds_write_b128 v245, v[8:11] offset:128
	ds_write_b128 v245, v[12:15] offset:192
	ds_write_b128 v245, v[16:19] offset:4352
	ds_write_b128 v245, v[20:23] offset:4416
	ds_write_b128 v245, v[24:27] offset:4480
	ds_write_b128 v245, v[28:31] offset:4544
	ds_write_b128 v245, v[32:35] offset:8704
	ds_write_b128 v245, v[36:39] offset:8768
	ds_write_b128 v245, v[40:43] offset:8832
	ds_write_b128 v245, v[44:47] offset:8896
	ds_write_b128 v245, v[48:51] offset:13056
	ds_write_b128 v245, v[52:55] offset:13120
	ds_write_b128 v245, v[56:59] offset:13184
	ds_write_b128 v245, v[60:63] offset:13248
	global_load_dwordx4 v[128:131], v247, s[0:1] nt
	s_add_u32 s0, s0, 0x4000
	s_addc_u32 s1, s1, 0
	global_load_dwordx4 v[132:135], v247, s[0:1] nt
	s_add_u32 s0, s0, 0x4000
	s_addc_u32 s1, s1, 0
	global_load_dwordx4 v[136:139], v247, s[0:1] nt
	s_add_u32 s0, s0, 0x4000
	s_addc_u32 s1, s1, 0
	global_load_dwordx4 v[140:143], v247, s[0:1] nt
	s_add_u32 s0, s0, 0x4000
	s_addc_u32 s1, s1, 0
	global_load_dwordx4 v[144:147], v247, s[0:1] nt
	s_add_u32 s0, s0, 0x4000
	s_addc_u32 s1, s1, 0
	global_load_dwordx4 v[148:151], v247, s[0:1] nt
	s_add_u32 s0, s0, 0x4000
	s_addc_u32 s1, s1, 0
	global_load_dwordx4 v[152:155], v247, s[0:1] nt
	s_add_u32 s0, s0, 0x4000
	s_addc_u32 s1, s1, 0
	global_load_dwordx4 v[156:159], v247, s[0:1] nt
	s_add_u32 s0, s0, 0x4000
	s_addc_u32 s1, s1, 0
	s_waitcnt lgkmcnt(0)
	ds_read_b128 v[160:163], v246
	ds_read_b128 v[164:167], v246 offset:1088
	ds_read_b128 v[168:171], v246 offset:2176
	ds_read_b128 v[172:175], v246 offset:3264
	ds_read_b128 v[176:179], v246 offset:4352
	ds_read_b128 v[180:183], v246 offset:5440
	ds_read_b128 v[184:187], v246 offset:6528
	ds_read_b128 v[188:191], v246 offset:7616
	s_waitcnt vmcnt(7) lgkmcnt(7)
	v_pk_add_f32 v[128:129], v[128:129], v[160:161]
	v_pk_add_f32 v[130:131], v[130:131], v[162:163]
	global_store_dwordx4 v247, v[128:131], s[4:5] nt
	s_add_u32 s4, s4, 0x4000
	s_addc_u32 s5, s5, 0
	s_waitcnt vmcnt(7) lgkmcnt(6)
	v_pk_add_f32 v[132:133], v[132:133], v[164:165]
	v_pk_add_f32 v[134:135], v[134:135], v[166:167]
	global_store_dwordx4 v247, v[132:135], s[4:5] nt
	s_add_u32 s4, s4, 0x4000
	s_addc_u32 s5, s5, 0
	s_waitcnt vmcnt(7) lgkmcnt(5)
	v_pk_add_f32 v[136:137], v[136:137], v[168:169]
	v_pk_add_f32 v[138:139], v[138:139], v[170:171]
	global_store_dwordx4 v247, v[136:139], s[4:5] nt
	s_add_u32 s4, s4, 0x4000
	s_addc_u32 s5, s5, 0
	s_waitcnt vmcnt(7) lgkmcnt(4)
	v_pk_add_f32 v[140:141], v[140:141], v[172:173]
	v_pk_add_f32 v[142:143], v[142:143], v[174:175]
	global_store_dwordx4 v247, v[140:143], s[4:5] nt
	s_add_u32 s4, s4, 0x4000
	s_addc_u32 s5, s5, 0
	s_waitcnt vmcnt(7) lgkmcnt(3)
	v_pk_add_f32 v[144:145], v[144:145], v[176:177]
	v_pk_add_f32 v[146:147], v[146:147], v[178:179]
	global_store_dwordx4 v247, v[144:147], s[4:5] nt
	s_add_u32 s4, s4, 0x4000
	s_addc_u32 s5, s5, 0
	s_waitcnt vmcnt(7) lgkmcnt(2)
	v_pk_add_f32 v[148:149], v[148:149], v[180:181]
	v_pk_add_f32 v[150:151], v[150:151], v[182:183]
	global_store_dwordx4 v247, v[148:151], s[4:5] nt
	s_add_u32 s4, s4, 0x4000
	s_addc_u32 s5, s5, 0
	s_waitcnt vmcnt(7) lgkmcnt(1)
	v_pk_add_f32 v[152:153], v[152:153], v[184:185]
	v_pk_add_f32 v[154:155], v[154:155], v[186:187]
	global_store_dwordx4 v247, v[152:155], s[4:5] nt
	s_add_u32 s4, s4, 0x4000
	s_addc_u32 s5, s5, 0
	s_waitcnt vmcnt(7) lgkmcnt(0)
	v_pk_add_f32 v[156:157], v[156:157], v[188:189]
	v_pk_add_f32 v[158:159], v[158:159], v[190:191]
	global_store_dwordx4 v247, v[156:159], s[4:5] nt
	s_add_u32 s4, s4, 0x4000
	s_addc_u32 s5, s5, 0
	s_nop 1
	global_load_dwordx4 v[128:131], v247, s[0:1] nt
	s_add_u32 s0, s0, 0x4000
	s_addc_u32 s1, s1, 0
	global_load_dwordx4 v[132:135], v247, s[0:1] nt
	s_add_u32 s0, s0, 0x4000
	s_addc_u32 s1, s1, 0
	global_load_dwordx4 v[136:139], v247, s[0:1] nt
	s_add_u32 s0, s0, 0x4000
	s_addc_u32 s1, s1, 0
	global_load_dwordx4 v[140:143], v247, s[0:1] nt
	s_add_u32 s0, s0, 0x4000
	s_addc_u32 s1, s1, 0
	global_load_dwordx4 v[144:147], v247, s[0:1] nt
	s_add_u32 s0, s0, 0x4000
	s_addc_u32 s1, s1, 0
	global_load_dwordx4 v[148:151], v247, s[0:1] nt
	s_add_u32 s0, s0, 0x4000
	s_addc_u32 s1, s1, 0
	global_load_dwordx4 v[152:155], v247, s[0:1] nt
	s_add_u32 s0, s0, 0x4000
	s_addc_u32 s1, s1, 0
	global_load_dwordx4 v[156:159], v247, s[0:1] nt
	s_add_u32 s0, s0, 0x4000
	s_addc_u32 s1, s1, 0
	ds_read_b128 v[160:163], v246 offset:8704
	ds_read_b128 v[164:167], v246 offset:9792
	ds_read_b128 v[168:171], v246 offset:10880
	ds_read_b128 v[172:175], v246 offset:11968
	ds_read_b128 v[176:179], v246 offset:13056
	ds_read_b128 v[180:183], v246 offset:14144
	ds_read_b128 v[184:187], v246 offset:15232
	ds_read_b128 v[188:191], v246 offset:16320
	s_waitcnt vmcnt(7) lgkmcnt(7)
	v_pk_add_f32 v[128:129], v[128:129], v[160:161]
	v_pk_add_f32 v[130:131], v[130:131], v[162:163]
	global_store_dwordx4 v247, v[128:131], s[4:5] nt
	s_add_u32 s4, s4, 0x4000
	s_addc_u32 s5, s5, 0
	s_waitcnt vmcnt(7) lgkmcnt(6)
	v_pk_add_f32 v[132:133], v[132:133], v[164:165]
	v_pk_add_f32 v[134:135], v[134:135], v[166:167]
	global_store_dwordx4 v247, v[132:135], s[4:5] nt
	s_add_u32 s4, s4, 0x4000
	s_addc_u32 s5, s5, 0
	s_waitcnt vmcnt(7) lgkmcnt(5)
	v_pk_add_f32 v[136:137], v[136:137], v[168:169]
	v_pk_add_f32 v[138:139], v[138:139], v[170:171]
	global_store_dwordx4 v247, v[136:139], s[4:5] nt
	s_add_u32 s4, s4, 0x4000
	s_addc_u32 s5, s5, 0
	s_waitcnt vmcnt(7) lgkmcnt(4)
; #define PH(k) case k: if (ONLY_PHASE >= 0 && ONLY_PHASE != k) break;
; template <int ph> DI void run_phase(const Ctx& c, char* smem) {
;     ...
;     PH(9) gemm_phase(smem, (const bf16_t*)(ws + OFF_R1), 4096, 1 << 30, XN, 1024, (const bf16_t*)(ws + OFF_W2), 4096, 8, EpiResid{p.out, p.out}, TIDX); break;
	v_pk_add_f32 v[140:141], v[140:141], v[172:173]
	v_pk_add_f32 v[142:143], v[142:143], v[174:175]
	global_store_dwordx4 v247, v[140:143], s[4:5] nt
	s_add_u32 s4, s4, 0x4000
	s_addc_u32 s5, s5, 0
	s_waitcnt vmcnt(7) lgkmcnt(3)
	v_pk_add_f32 v[144:145], v[144:145], v[176:177]
	v_pk_add_f32 v[146:147], v[146:147], v[178:179]
	global_store_dwordx4 v247, v[144:147], s[4:5] nt
	s_add_u32 s4, s4, 0x4000
	s_addc_u32 s5, s5, 0
	s_waitcnt vmcnt(7) lgkmcnt(2)
	v_pk_add_f32 v[148:149], v[148:149], v[180:181]
	v_pk_add_f32 v[150:151], v[150:151], v[182:183]
	global_store_dwordx4 v247, v[148:151], s[4:5] nt
	s_add_u32 s4, s4, 0x4000
	s_addc_u32 s5, s5, 0
	s_waitcnt vmcnt(7) lgkmcnt(1)
	v_pk_add_f32 v[152:153], v[152:153], v[184:185]
	v_pk_add_f32 v[154:155], v[154:155], v[186:187]
	global_store_dwordx4 v247, v[152:155], s[4:5] nt
	s_add_u32 s4, s4, 0x4000
	s_addc_u32 s5, s5, 0
	s_waitcnt vmcnt(7) lgkmcnt(0)
	v_pk_add_f32 v[156:157], v[156:157], v[188:189]
	v_pk_add_f32 v[158:159], v[158:159], v[190:191]
	global_store_dwordx4 v247, v[156:159], s[4:5] nt
	s_add_u32 s4, s4, 0x4000
	s_addc_u32 s5, s5, 0
	s_nop 1
	s_waitcnt lgkmcnt(0)
	ds_write_b128 v245, v[64:67]
	ds_write_b128 v245, v[68:71] offset:64
	ds_write_b128 v245, v[72:75] offset:128
	ds_write_b128 v245, v[76:79] offset:192
	ds_write_b128 v245, v[80:83] offset:4352
	ds_write_b128 v245, v[84:87] offset:4416
	ds_write_b128 v245, v[88:91] offset:4480
	ds_write_b128 v245, v[92:95] offset:4544
	ds_write_b128 v245, v[96:99] offset:8704
	ds_write_b128 v245, v[100:103] offset:8768
	ds_write_b128 v245, v[104:107] offset:8832
	ds_write_b128 v245, v[108:111] offset:8896
	ds_write_b128 v245, v[112:115] offset:13056
	ds_write_b128 v245, v[116:119] offset:13120
	ds_write_b128 v245, v[120:123] offset:13184
	ds_write_b128 v245, v[124:127] offset:13248
	global_load_dwordx4 v[128:131], v247, s[0:1] nt
	s_add_u32 s0, s0, 0x4000
	s_addc_u32 s1, s1, 0
	global_load_dwordx4 v[132:135], v247, s[0:1] nt
	s_add_u32 s0, s0, 0x4000
	s_addc_u32 s1, s1, 0
	global_load_dwordx4 v[136:139], v247, s[0:1] nt
	s_add_u32 s0, s0, 0x4000
	s_addc_u32 s1, s1, 0
	global_load_dwordx4 v[140:143], v247, s[0:1] nt
	s_add_u32 s0, s0, 0x4000
	s_addc_u32 s1, s1, 0
	global_load_dwordx4 v[144:147], v247, s[0:1] nt
	s_add_u32 s0, s0, 0x4000
	s_addc_u32 s1, s1, 0
	global_load_dwordx4 v[148:151], v247, s[0:1] nt
	s_add_u32 s0, s0, 0x4000
	s_addc_u32 s1, s1, 0
	global_load_dwordx4 v[152:155], v247, s[0:1] nt
	s_add_u32 s0, s0, 0x4000
	s_addc_u32 s1, s1, 0
	global_load_dwordx4 v[156:159], v247, s[0:1] nt
	s_add_u32 s0, s0, 0x4000
	s_addc_u32 s1, s1, 0
	s_waitcnt lgkmcnt(0)
	ds_read_b128 v[160:163], v246
	ds_read_b128 v[164:167], v246 offset:1088
	ds_read_b128 v[168:171], v246 offset:2176
	ds_read_b128 v[172:175], v246 offset:3264
	ds_read_b128 v[176:179], v246 offset:4352
	ds_read_b128 v[180:183], v246 offset:5440
	ds_read_b128 v[184:187], v246 offset:6528
	ds_read_b128 v[188:191], v246 offset:7616
	s_waitcnt vmcnt(7) lgkmcnt(7)
	v_pk_add_f32 v[128:129], v[128:129], v[160:161]
	v_pk_add_f32 v[130:131], v[130:131], v[162:163]
	global_store_dwordx4 v247, v[128:131], s[4:5] nt
	s_add_u32 s4, s4, 0x4000
	s_addc_u32 s5, s5, 0
	s_waitcnt vmcnt(7) lgkmcnt(6)
	v_pk_add_f32 v[132:133], v[132:133], v[164:165]
	v_pk_add_f32 v[134:135], v[134:135], v[166:167]
	global_store_dwordx4 v247, v[132:135], s[4:5] nt
	s_add_u32 s4, s4, 0x4000
	s_addc_u32 s5, s5, 0
	s_waitcnt vmcnt(7) lgkmcnt(5)
	v_pk_add_f32 v[136:137], v[136:137], v[168:169]
	v_pk_add_f32 v[138:139], v[138:139], v[170:171]
	global_store_dwordx4 v247, v[136:139], s[4:5] nt
	s_add_u32 s4, s4, 0x4000
	s_addc_u32 s5, s5, 0
	s_waitcnt vmcnt(7) lgkmcnt(4)
	v_pk_add_f32 v[140:141], v[140:141], v[172:173]
	v_pk_add_f32 v[142:143], v[142:143], v[174:175]
	global_store_dwordx4 v247, v[140:143], s[4:5] nt
	s_add_u32 s4, s4, 0x4000
	s_addc_u32 s5, s5, 0
	s_waitcnt vmcnt(7) lgkmcnt(3)
; #define PH(k) case k: if (ONLY_PHASE >= 0 && ONLY_PHASE != k) break;
; template <int ph> DI void run_phase(const Ctx& c, char* smem) {
;     ...
;     PH(9) gemm_phase(smem, (const bf16_t*)(ws + OFF_R1), 4096, 1 << 30, XN, 1024, (const bf16_t*)(ws + OFF_W2), 4096, 8, EpiResid{p.out, p.out}, TIDX); break;
	v_pk_add_f32 v[144:145], v[144:145], v[176:177]
	v_pk_add_f32 v[146:147], v[146:147], v[178:179]
	global_store_dwordx4 v247, v[144:147], s[4:5] nt
	s_add_u32 s4, s4, 0x4000
	s_addc_u32 s5, s5, 0
	s_waitcnt vmcnt(7) lgkmcnt(2)
	v_pk_add_f32 v[148:149], v[148:149], v[180:181]
	v_pk_add_f32 v[150:151], v[150:151], v[182:183]
	global_store_dwordx4 v247, v[148:151], s[4:5] nt
	s_add_u32 s4, s4, 0x4000
	s_addc_u32 s5, s5, 0
	s_waitcnt vmcnt(7) lgkmcnt(1)
	v_pk_add_f32 v[152:153], v[152:153], v[184:185]
	v_pk_add_f32 v[154:155], v[154:155], v[186:187]
	global_store_dwordx4 v247, v[152:155], s[4:5] nt
	s_add_u32 s4, s4, 0x4000
	s_addc_u32 s5, s5, 0
	s_waitcnt vmcnt(7) lgkmcnt(0)
	v_pk_add_f32 v[156:157], v[156:157], v[188:189]
	v_pk_add_f32 v[158:159], v[158:159], v[190:191]
	global_store_dwordx4 v247, v[156:159], s[4:5] nt
	s_add_u32 s4, s4, 0x4000
	s_addc_u32 s5, s5, 0
	s_nop 1
	global_load_dwordx4 v[128:131], v247, s[0:1] nt
	s_add_u32 s0, s0, 0x4000
	s_addc_u32 s1, s1, 0
	global_load_dwordx4 v[132:135], v247, s[0:1] nt
	s_add_u32 s0, s0, 0x4000
	s_addc_u32 s1, s1, 0
	global_load_dwordx4 v[136:139], v247, s[0:1] nt
	s_add_u32 s0, s0, 0x4000
	s_addc_u32 s1, s1, 0
	global_load_dwordx4 v[140:143], v247, s[0:1] nt
	s_add_u32 s0, s0, 0x4000
	s_addc_u32 s1, s1, 0
	global_load_dwordx4 v[144:147], v247, s[0:1] nt
	s_add_u32 s0, s0, 0x4000
	s_addc_u32 s1, s1, 0
	global_load_dwordx4 v[148:151], v247, s[0:1] nt
	s_add_u32 s0, s0, 0x4000
	s_addc_u32 s1, s1, 0
	global_load_dwordx4 v[152:155], v247, s[0:1] nt
	s_add_u32 s0, s0, 0x4000
	s_addc_u32 s1, s1, 0
	global_load_dwordx4 v[156:159], v247, s[0:1] nt
	s_add_u32 s0, s0, 0x4000
	s_addc_u32 s1, s1, 0
	ds_read_b128 v[160:163], v246 offset:8704
	ds_read_b128 v[164:167], v246 offset:9792
	ds_read_b128 v[168:171], v246 offset:10880
	ds_read_b128 v[172:175], v246 offset:11968
	ds_read_b128 v[176:179], v246 offset:13056
	ds_read_b128 v[180:183], v246 offset:14144
	ds_read_b128 v[184:187], v246 offset:15232
	ds_read_b128 v[188:191], v246 offset:16320
	s_waitcnt vmcnt(7) lgkmcnt(7)
	v_pk_add_f32 v[128:129], v[128:129], v[160:161]
	v_pk_add_f32 v[130:131], v[130:131], v[162:163]
	global_store_dwordx4 v247, v[128:131], s[4:5] nt
	s_add_u32 s4, s4, 0x4000
	s_addc_u32 s5, s5, 0
	s_waitcnt vmcnt(7) lgkmcnt(6)
	v_pk_add_f32 v[132:133], v[132:133], v[164:165]
	v_pk_add_f32 v[134:135], v[134:135], v[166:167]
	global_store_dwordx4 v247, v[132:135], s[4:5] nt
	s_add_u32 s4, s4, 0x4000
	s_addc_u32 s5, s5, 0
	s_waitcnt vmcnt(7) lgkmcnt(5)
	v_pk_add_f32 v[136:137], v[136:137], v[168:169]
	v_pk_add_f32 v[138:139], v[138:139], v[170:171]
	global_store_dwordx4 v247, v[136:139], s[4:5] nt
	s_add_u32 s4, s4, 0x4000
	s_addc_u32 s5, s5, 0
	s_waitcnt vmcnt(7) lgkmcnt(4)
	v_pk_add_f32 v[140:141], v[140:141], v[172:173]
	v_pk_add_f32 v[142:143], v[142:143], v[174:175]
	global_store_dwordx4 v247, v[140:143], s[4:5] nt
	s_add_u32 s4, s4, 0x4000
	s_addc_u32 s5, s5, 0
	s_waitcnt vmcnt(7) lgkmcnt(3)
	v_pk_add_f32 v[144:145], v[144:145], v[176:177]
	v_pk_add_f32 v[146:147], v[146:147], v[178:179]
	global_store_dwordx4 v247, v[144:147], s[4:5] nt
	s_add_u32 s4, s4, 0x4000
	s_addc_u32 s5, s5, 0
	s_waitcnt vmcnt(7) lgkmcnt(2)
	v_pk_add_f32 v[148:149], v[148:149], v[180:181]
	v_pk_add_f32 v[150:151], v[150:151], v[182:183]
	global_store_dwordx4 v247, v[148:151], s[4:5] nt
	s_add_u32 s4, s4, 0x4000
	s_addc_u32 s5, s5, 0
	s_waitcnt vmcnt(7) lgkmcnt(1)
	v_pk_add_f32 v[152:153], v[152:153], v[184:185]
	v_pk_add_f32 v[154:155], v[154:155], v[186:187]
	global_store_dwordx4 v247, v[152:155], s[4:5] nt
	s_add_u32 s4, s4, 0x4000
	s_addc_u32 s5, s5, 0
	s_waitcnt vmcnt(7) lgkmcnt(0)
	v_pk_add_f32 v[156:157], v[156:157], v[188:189]
	v_pk_add_f32 v[158:159], v[158:159], v[190:191]
	global_store_dwordx4 v247, v[156:159], s[4:5] nt
	s_add_u32 s4, s4, 0x4000
	s_addc_u32 s5, s5, 0
	s_nop 1
	s_add_u32 s15, s15, 64
	s_branch .Lg9_tile

; #define PH(k) case k: if (ONLY_PHASE >= 0 && ONLY_PHASE != k) break;
; template <int ph> DI void run_phase(const Ctx& c, char* smem) {
;     ...
;     PH(15) gemm_phase(smem, (const bf16_t*)(ws + OFF_S5Y), 512, 512, (const bf16_t*)(ws + OFF_MLRAW) + 1024, 2080, (const bf16_t*)(ws + OFF_WCDOUT), 1536, 8, EpiResid{p.out, p.out}, TIDX); break;
.Lg15_epi:
	s_nop 7
	s_nop 7
	s_lshl_b32 s20, s98, 12
	s_lshl_b32 s19, s21, 2
	s_add_u32 s20, s20, s19
	s_add_u32 s4, s6, s20
	s_addc_u32 s5, s7, 0
	s_lshl_b32 s20, s98, 12
	s_lshl_b32 s19, s21, 2
	s_add_u32 s20, s20, s19
	s_add_u32 s0, s6, s20
	s_addc_u32 s1, s7, 0
	ds_write_b128 v245, v[0:3]
	ds_write_b128 v245, v[4:7] offset:64
	ds_write_b128 v245, v[8:11] offset:128
	ds_write_b128 v245, v[12:15] offset:192
	ds_write_b128 v245, v[16:19] offset:4352
	ds_write_b128 v245, v[20:23] offset:4416
	ds_write_b128 v245, v[24:27] offset:4480
	ds_write_b128 v245, v[28:31] offset:4544
	ds_write_b128 v245, v[32:35] offset:8704
	ds_write_b128 v245, v[36:39] offset:8768
	ds_write_b128 v245, v[40:43] offset:8832
	ds_write_b128 v245, v[44:47] offset:8896
	ds_write_b128 v245, v[48:51] offset:13056
	ds_write_b128 v245, v[52:55] offset:13120
	ds_write_b128 v245, v[56:59] offset:13184
	ds_write_b128 v245, v[60:63] offset:13248
	global_load_dwordx4 v[128:131], v247, s[0:1] nt
	s_add_u32 s0, s0, 0x4000
	s_addc_u32 s1, s1, 0
	global_load_dwordx4 v[132:135], v247, s[0:1] nt
	s_add_u32 s0, s0, 0x4000
	s_addc_u32 s1, s1, 0
	global_load_dwordx4 v[136:139], v247, s[0:1] nt
	s_add_u32 s0, s0, 0x4000
	s_addc_u32 s1, s1, 0
	global_load_dwordx4 v[140:143], v247, s[0:1] nt
	s_add_u32 s0, s0, 0x4000
	s_addc_u32 s1, s1, 0
	global_load_dwordx4 v[144:147], v247, s[0:1] nt
	s_add_u32 s0, s0, 0x4000
	s_addc_u32 s1, s1, 0
	global_load_dwordx4 v[148:151], v247, s[0:1] nt
	s_add_u32 s0, s0, 0x4000
	s_addc_u32 s1, s1, 0
	global_load_dwordx4 v[152:155], v247, s[0:1] nt
	s_add_u32 s0, s0, 0x4000
	s_addc_u32 s1, s1, 0
	global_load_dwordx4 v[156:159], v247, s[0:1] nt
	s_add_u32 s0, s0, 0x4000
	s_addc_u32 s1, s1, 0
	s_waitcnt lgkmcnt(0)
	ds_read_b128 v[160:163], v246
	ds_read_b128 v[164:167], v246 offset:1088
	ds_read_b128 v[168:171], v246 offset:2176
	ds_read_b128 v[172:175], v246 offset:3264
	ds_read_b128 v[176:179], v246 offset:4352
	ds_read_b128 v[180:183], v246 offset:5440
	ds_read_b128 v[184:187], v246 offset:6528
	ds_read_b128 v[188:191], v246 offset:7616
	s_waitcnt vmcnt(7) lgkmcnt(7)
	v_pk_add_f32 v[128:129], v[128:129], v[160:161]
	v_pk_add_f32 v[130:131], v[130:131], v[162:163]
	global_store_dwordx4 v247, v[128:131], s[4:5] nt
	s_add_u32 s4, s4, 0x4000
	s_addc_u32 s5, s5, 0
	s_waitcnt vmcnt(7) lgkmcnt(6)
	v_pk_add_f32 v[132:133], v[132:133], v[164:165]
	v_pk_add_f32 v[134:135], v[134:135], v[166:167]
	global_store_dwordx4 v247, v[132:135], s[4:5] nt
	s_add_u32 s4, s4, 0x4000
	s_addc_u32 s5, s5, 0
	s_waitcnt vmcnt(7) lgkmcnt(5)
	v_pk_add_f32 v[136:137], v[136:137], v[168:169]
	v_pk_add_f32 v[138:139], v[138:139], v[170:171]
	global_store_dwordx4 v247, v[136:139], s[4:5] nt
	s_add_u32 s4, s4, 0x4000
	s_addc_u32 s5, s5, 0
	s_waitcnt vmcnt(7) lgkmcnt(4)
	v_pk_add_f32 v[140:141], v[140:141], v[172:173]
	v_pk_add_f32 v[142:143], v[142:143], v[174:175]
	global_store_dwordx4 v247, v[140:143], s[4:5] nt
	s_add_u32 s4, s4, 0x4000
	s_addc_u32 s5, s5, 0
	s_waitcnt vmcnt(7) lgkmcnt(3)
	v_pk_add_f32 v[144:145], v[144:145], v[176:177]
	v_pk_add_f32 v[146:147], v[146:147], v[178:179]
	global_store_dwordx4 v247, v[144:147], s[4:5] nt
	s_add_u32 s4, s4, 0x4000
	s_addc_u32 s5, s5, 0
	s_waitcnt vmcnt(7) lgkmcnt(2)
	v_pk_add_f32 v[148:149], v[148:149], v[180:181]
	v_pk_add_f32 v[150:151], v[150:151], v[182:183]
	global_store_dwordx4 v247, v[148:151], s[4:5] nt
	s_add_u32 s4, s4, 0x4000
	s_addc_u32 s5, s5, 0
	s_waitcnt vmcnt(7) lgkmcnt(1)
	v_pk_add_f32 v[152:153], v[152:153], v[184:185]
	v_pk_add_f32 v[154:155], v[154:155], v[186:187]
	global_store_dwordx4 v247, v[152:155], s[4:5] nt
	s_add_u32 s4, s4, 0x4000
	s_addc_u32 s5, s5, 0
	s_waitcnt vmcnt(7) lgkmcnt(0)
	v_pk_add_f32 v[156:157], v[156:157], v[188:189]
	v_pk_add_f32 v[158:159], v[158:159], v[190:191]
	global_store_dwordx4 v247, v[156:159], s[4:5] nt
	s_add_u32 s4, s4, 0x4000
	s_addc_u32 s5, s5, 0
	s_nop 1
	global_load_dwordx4 v[128:131], v247, s[0:1] nt
	s_add_u32 s0, s0, 0x4000
	s_addc_u32 s1, s1, 0
	global_load_dwordx4 v[132:135], v247, s[0:1] nt
	s_add_u32 s0, s0, 0x4000
	s_addc_u32 s1, s1, 0
	global_load_dwordx4 v[136:139], v247, s[0:1] nt
	s_add_u32 s0, s0, 0x4000
	s_addc_u32 s1, s1, 0
	global_load_dwordx4 v[140:143], v247, s[0:1] nt
	s_add_u32 s0, s0, 0x4000
	s_addc_u32 s1, s1, 0
	global_load_dwordx4 v[144:147], v247, s[0:1] nt
	s_add_u32 s0, s0, 0x4000
	s_addc_u32 s1, s1, 0
	global_load_dwordx4 v[148:151], v247, s[0:1] nt
	s_add_u32 s0, s0, 0x4000
	s_addc_u32 s1, s1, 0
	global_load_dwordx4 v[152:155], v247, s[0:1] nt
	s_add_u32 s0, s0, 0x4000
	s_addc_u32 s1, s1, 0
	global_load_dwordx4 v[156:159], v247, s[0:1] nt
	s_add_u32 s0, s0, 0x4000
	s_addc_u32 s1, s1, 0
	ds_read_b128 v[160:163], v246 offset:8704
	ds_read_b128 v[164:167], v246 offset:9792
	ds_read_b128 v[168:171], v246 offset:10880
	ds_read_b128 v[172:175], v246 offset:11968
	ds_read_b128 v[176:179], v246 offset:13056
	ds_read_b128 v[180:183], v246 offset:14144
	ds_read_b128 v[184:187], v246 offset:15232
	ds_read_b128 v[188:191], v246 offset:16320
	s_waitcnt vmcnt(7) lgkmcnt(7)
	v_pk_add_f32 v[128:129], v[128:129], v[160:161]
	v_pk_add_f32 v[130:131], v[130:131], v[162:163]
	global_store_dwordx4 v247, v[128:131], s[4:5] nt
	s_add_u32 s4, s4, 0x4000
	s_addc_u32 s5, s5, 0
	s_waitcnt vmcnt(7) lgkmcnt(6)
	v_pk_add_f32 v[132:133], v[132:133], v[164:165]
	v_pk_add_f32 v[134:135], v[134:135], v[166:167]
	global_store_dwordx4 v247, v[132:135], s[4:5] nt
	s_add_u32 s4, s4, 0x4000
	s_addc_u32 s5, s5, 0
	s_waitcnt vmcnt(7) lgkmcnt(5)
	v_pk_add_f32 v[136:137], v[136:137], v[168:169]
	v_pk_add_f32 v[138:139], v[138:139], v[170:171]
	global_store_dwordx4 v247, v[136:139], s[4:5] nt
	s_add_u32 s4, s4, 0x4000
	s_addc_u32 s5, s5, 0
	s_waitcnt vmcnt(7) lgkmcnt(4)
; #define PH(k) case k: if (ONLY_PHASE >= 0 && ONLY_PHASE != k) break;
; template <int ph> DI void run_phase(const Ctx& c, char* smem) {
;     ...
;     PH(15) gemm_phase(smem, (const bf16_t*)(ws + OFF_S5Y), 512, 512, (const bf16_t*)(ws + OFF_MLRAW) + 1024, 2080, (const bf16_t*)(ws + OFF_WCDOUT), 1536, 8, EpiResid{p.out, p.out}, TIDX); break;
	v_pk_add_f32 v[140:141], v[140:141], v[172:173]
	v_pk_add_f32 v[142:143], v[142:143], v[174:175]
	global_store_dwordx4 v247, v[140:143], s[4:5] nt
	s_add_u32 s4, s4, 0x4000
	s_addc_u32 s5, s5, 0
	s_waitcnt vmcnt(7) lgkmcnt(3)
	v_pk_add_f32 v[144:145], v[144:145], v[176:177]
	v_pk_add_f32 v[146:147], v[146:147], v[178:179]
	global_store_dwordx4 v247, v[144:147], s[4:5] nt
	s_add_u32 s4, s4, 0x4000
	s_addc_u32 s5, s5, 0
	s_waitcnt vmcnt(7) lgkmcnt(2)
	v_pk_add_f32 v[148:149], v[148:149], v[180:181]
	v_pk_add_f32 v[150:151], v[150:151], v[182:183]
	global_store_dwordx4 v247, v[148:151], s[4:5] nt
	s_add_u32 s4, s4, 0x4000
	s_addc_u32 s5, s5, 0
	s_waitcnt vmcnt(7) lgkmcnt(1)
	v_pk_add_f32 v[152:153], v[152:153], v[184:185]
	v_pk_add_f32 v[154:155], v[154:155], v[186:187]
	global_store_dwordx4 v247, v[152:155], s[4:5] nt
	s_add_u32 s4, s4, 0x4000
	s_addc_u32 s5, s5, 0
	s_waitcnt vmcnt(7) lgkmcnt(0)
	v_pk_add_f32 v[156:157], v[156:157], v[188:189]
	v_pk_add_f32 v[158:159], v[158:159], v[190:191]
	global_store_dwordx4 v247, v[156:159], s[4:5] nt
	s_add_u32 s4, s4, 0x4000
	s_addc_u32 s5, s5, 0
	s_nop 1
	s_waitcnt lgkmcnt(0)
	ds_write_b128 v245, v[64:67]
	ds_write_b128 v245, v[68:71] offset:64
	ds_write_b128 v245, v[72:75] offset:128
	ds_write_b128 v245, v[76:79] offset:192
	ds_write_b128 v245, v[80:83] offset:4352
	ds_write_b128 v245, v[84:87] offset:4416
	ds_write_b128 v245, v[88:91] offset:4480
	ds_write_b128 v245, v[92:95] offset:4544
	ds_write_b128 v245, v[96:99] offset:8704
	ds_write_b128 v245, v[100:103] offset:8768
	ds_write_b128 v245, v[104:107] offset:8832
	ds_write_b128 v245, v[108:111] offset:8896
	ds_write_b128 v245, v[112:115] offset:13056
	ds_write_b128 v245, v[116:119] offset:13120
	ds_write_b128 v245, v[120:123] offset:13184
	ds_write_b128 v245, v[124:127] offset:13248
	global_load_dwordx4 v[128:131], v247, s[0:1] nt
	s_add_u32 s0, s0, 0x4000
	s_addc_u32 s1, s1, 0
	global_load_dwordx4 v[132:135], v247, s[0:1] nt
	s_add_u32 s0, s0, 0x4000
	s_addc_u32 s1, s1, 0
	global_load_dwordx4 v[136:139], v247, s[0:1] nt
	s_add_u32 s0, s0, 0x4000
	s_addc_u32 s1, s1, 0
	global_load_dwordx4 v[140:143], v247, s[0:1] nt
	s_add_u32 s0, s0, 0x4000
	s_addc_u32 s1, s1, 0
	global_load_dwordx4 v[144:147], v247, s[0:1] nt
	s_add_u32 s0, s0, 0x4000
	s_addc_u32 s1, s1, 0
	global_load_dwordx4 v[148:151], v247, s[0:1] nt
	s_add_u32 s0, s0, 0x4000
	s_addc_u32 s1, s1, 0
	global_load_dwordx4 v[152:155], v247, s[0:1] nt
	s_add_u32 s0, s0, 0x4000
	s_addc_u32 s1, s1, 0
	global_load_dwordx4 v[156:159], v247, s[0:1] nt
	s_add_u32 s0, s0, 0x4000
	s_addc_u32 s1, s1, 0
	s_waitcnt lgkmcnt(0)
	ds_read_b128 v[160:163], v246
	ds_read_b128 v[164:167], v246 offset:1088
	ds_read_b128 v[168:171], v246 offset:2176
	ds_read_b128 v[172:175], v246 offset:3264
	ds_read_b128 v[176:179], v246 offset:4352
	ds_read_b128 v[180:183], v246 offset:5440
	ds_read_b128 v[184:187], v246 offset:6528
	ds_read_b128 v[188:191], v246 offset:7616
	s_waitcnt vmcnt(7) lgkmcnt(7)
	v_pk_add_f32 v[128:129], v[128:129], v[160:161]
	v_pk_add_f32 v[130:131], v[130:131], v[162:163]
	global_store_dwordx4 v247, v[128:131], s[4:5] nt
	s_add_u32 s4, s4, 0x4000
	s_addc_u32 s5, s5, 0
	s_waitcnt vmcnt(7) lgkmcnt(6)
	v_pk_add_f32 v[132:133], v[132:133], v[164:165]
	v_pk_add_f32 v[134:135], v[134:135], v[166:167]
	global_store_dwordx4 v247, v[132:135], s[4:5] nt
	s_add_u32 s4, s4, 0x4000
	s_addc_u32 s5, s5, 0
	s_waitcnt vmcnt(7) lgkmcnt(5)
	v_pk_add_f32 v[136:137], v[136:137], v[168:169]
	v_pk_add_f32 v[138:139], v[138:139], v[170:171]
	global_store_dwordx4 v247, v[136:139], s[4:5] nt
	s_add_u32 s4, s4, 0x4000
	s_addc_u32 s5, s5, 0
	s_waitcnt vmcnt(7) lgkmcnt(4)
	v_pk_add_f32 v[140:141], v[140:141], v[172:173]
	v_pk_add_f32 v[142:143], v[142:143], v[174:175]
	global_store_dwordx4 v247, v[140:143], s[4:5] nt
	s_add_u32 s4, s4, 0x4000
	s_addc_u32 s5, s5, 0
	s_waitcnt vmcnt(7) lgkmcnt(3)
; #define PH(k) case k: if (ONLY_PHASE >= 0 && ONLY_PHASE != k) break;
; template <int ph> DI void run_phase(const Ctx& c, char* smem) {
;     ...
;     PH(15) gemm_phase(smem, (const bf16_t*)(ws + OFF_S5Y), 512, 512, (const bf16_t*)(ws + OFF_MLRAW) + 1024, 2080, (const bf16_t*)(ws + OFF_WCDOUT), 1536, 8, EpiResid{p.out, p.out}, TIDX); break;
	v_pk_add_f32 v[144:145], v[144:145], v[176:177]
	v_pk_add_f32 v[146:147], v[146:147], v[178:179]
	global_store_dwordx4 v247, v[144:147], s[4:5] nt
	s_add_u32 s4, s4, 0x4000
	s_addc_u32 s5, s5, 0
	s_waitcnt vmcnt(7) lgkmcnt(2)
	v_pk_add_f32 v[148:149], v[148:149], v[180:181]
	v_pk_add_f32 v[150:151], v[150:151], v[182:183]
	global_store_dwordx4 v247, v[148:151], s[4:5] nt
	s_add_u32 s4, s4, 0x4000
	s_addc_u32 s5, s5, 0
	s_waitcnt vmcnt(7) lgkmcnt(1)
	v_pk_add_f32 v[152:153], v[152:153], v[184:185]
	v_pk_add_f32 v[154:155], v[154:155], v[186:187]
	global_store_dwordx4 v247, v[152:155], s[4:5] nt
	s_add_u32 s4, s4, 0x4000
	s_addc_u32 s5, s5, 0
	s_waitcnt vmcnt(7) lgkmcnt(0)
	v_pk_add_f32 v[156:157], v[156:157], v[188:189]
	v_pk_add_f32 v[158:159], v[158:159], v[190:191]
	global_store_dwordx4 v247, v[156:159], s[4:5] nt
	s_add_u32 s4, s4, 0x4000
	s_addc_u32 s5, s5, 0
	s_nop 1
	global_load_dwordx4 v[128:131], v247, s[0:1] nt
	s_add_u32 s0, s0, 0x4000
	s_addc_u32 s1, s1, 0
	global_load_dwordx4 v[132:135], v247, s[0:1] nt
	s_add_u32 s0, s0, 0x4000
	s_addc_u32 s1, s1, 0
	global_load_dwordx4 v[136:139], v247, s[0:1] nt
	s_add_u32 s0, s0, 0x4000
	s_addc_u32 s1, s1, 0
	global_load_dwordx4 v[140:143], v247, s[0:1] nt
	s_add_u32 s0, s0, 0x4000
	s_addc_u32 s1, s1, 0
	global_load_dwordx4 v[144:147], v247, s[0:1] nt
	s_add_u32 s0, s0, 0x4000
	s_addc_u32 s1, s1, 0
	global_load_dwordx4 v[148:151], v247, s[0:1] nt
	s_add_u32 s0, s0, 0x4000
	s_addc_u32 s1, s1, 0
	global_load_dwordx4 v[152:155], v247, s[0:1] nt
	s_add_u32 s0, s0, 0x4000
	s_addc_u32 s1, s1, 0
	global_load_dwordx4 v[156:159], v247, s[0:1] nt
	s_add_u32 s0, s0, 0x4000
	s_addc_u32 s1, s1, 0
	ds_read_b128 v[160:163], v246 offset:8704
	ds_read_b128 v[164:167], v246 offset:9792
	ds_read_b128 v[168:171], v246 offset:10880
	ds_read_b128 v[172:175], v246 offset:11968
	ds_read_b128 v[176:179], v246 offset:13056
	ds_read_b128 v[180:183], v246 offset:14144
	ds_read_b128 v[184:187], v246 offset:15232
	ds_read_b128 v[188:191], v246 offset:16320
	s_waitcnt vmcnt(7) lgkmcnt(7)
	v_pk_add_f32 v[128:129], v[128:129], v[160:161]
	v_pk_add_f32 v[130:131], v[130:131], v[162:163]
	global_store_dwordx4 v247, v[128:131], s[4:5] nt
	s_add_u32 s4, s4, 0x4000
	s_addc_u32 s5, s5, 0
	s_waitcnt vmcnt(7) lgkmcnt(6)
	v_pk_add_f32 v[132:133], v[132:133], v[164:165]
	v_pk_add_f32 v[134:135], v[134:135], v[166:167]
	global_store_dwordx4 v247, v[132:135], s[4:5] nt
	s_add_u32 s4, s4, 0x4000
	s_addc_u32 s5, s5, 0
	s_waitcnt vmcnt(7) lgkmcnt(5)
	v_pk_add_f32 v[136:137], v[136:137], v[168:169]
	v_pk_add_f32 v[138:139], v[138:139], v[170:171]
	global_store_dwordx4 v247, v[136:139], s[4:5] nt
	s_add_u32 s4, s4, 0x4000
	s_addc_u32 s5, s5, 0
	s_waitcnt vmcnt(7) lgkmcnt(4)
	v_pk_add_f32 v[140:141], v[140:141], v[172:173]
	v_pk_add_f32 v[142:143], v[142:143], v[174:175]
	global_store_dwordx4 v247, v[140:143], s[4:5] nt
	s_add_u32 s4, s4, 0x4000
	s_addc_u32 s5, s5, 0
	s_waitcnt vmcnt(7) lgkmcnt(3)
	v_pk_add_f32 v[144:145], v[144:145], v[176:177]
	v_pk_add_f32 v[146:147], v[146:147], v[178:179]
	global_store_dwordx4 v247, v[144:147], s[4:5] nt
	s_add_u32 s4, s4, 0x4000
	s_addc_u32 s5, s5, 0
	s_waitcnt vmcnt(7) lgkmcnt(2)
	v_pk_add_f32 v[148:149], v[148:149], v[180:181]
	v_pk_add_f32 v[150:151], v[150:151], v[182:183]
	global_store_dwordx4 v247, v[148:151], s[4:5] nt
	s_add_u32 s4, s4, 0x4000
	s_addc_u32 s5, s5, 0
	s_waitcnt vmcnt(7) lgkmcnt(1)
	v_pk_add_f32 v[152:153], v[152:153], v[184:185]
	v_pk_add_f32 v[154:155], v[154:155], v[186:187]
	global_store_dwordx4 v247, v[152:155], s[4:5] nt
	s_add_u32 s4, s4, 0x4000
	s_addc_u32 s5, s5, 0
	s_waitcnt vmcnt(7) lgkmcnt(0)
	v_pk_add_f32 v[156:157], v[156:157], v[188:189]
	v_pk_add_f32 v[158:159], v[158:159], v[190:191]
	global_store_dwordx4 v247, v[156:159], s[4:5] nt
	s_add_u32 s4, s4, 0x4000
	s_addc_u32 s5, s5, 0
	s_nop 1
	s_add_u32 s9, s9, 64
	s_branch .Lg15_tile
